# v33 plus code placement: the 12 GEMM K-loop heads and the 2 DSA score-loop heads aligned to 64 bytes
# baseline (speedup 1.0000x reference)
.LBB0_251:
	s_ashr_i32 s19, s18, 31
	s_lshl_b64 s[20:21], s[18:19], 19
	s_add_u32 s20, s30, s20
	s_addc_u32 s21, s31, s21
	s_and_b64 s[22:23], s[4:5], exec
	s_cselect_b32 s19, s21, s25
	s_cselect_b32 s53, s20, s24
	s_ashr_i32 s17, s16, 31
	s_lshl_b64 s[22:23], s[16:17], 19
	s_add_u32 s22, s33, s22
	s_addc_u32 s23, s34, s23
	s_and_b64 s[28:29], s[4:5], exec
	s_cselect_b32 s17, s23, s27
	s_cselect_b32 s54, s22, s26
	s_add_u32 s24, s24, 0x40080
	s_addc_u32 s25, s25, 0
	s_add_u32 s55, s26, 0x100
	v_mov_b32_e32 v2, 0
	s_addc_u32 s56, s27, 0
	s_mov_b32 s57, -2
	v_mov_b32_e32 v3, v2
	v_mov_b32_e32 v4, v2
	v_mov_b32_e32 v5, v2
	v_mov_b32_e32 v10, v2
	v_mov_b32_e32 v11, v2
	v_mov_b32_e32 v12, v2
	v_mov_b32_e32 v13, v2
	v_mov_b32_e32 v18, v2
	v_mov_b32_e32 v19, v2
	v_mov_b32_e32 v20, v2
	v_mov_b32_e32 v21, v2
	v_mov_b32_e32 v30, v2
	v_mov_b32_e32 v31, v2
	v_mov_b32_e32 v32, v2
	v_mov_b32_e32 v33, v2
	v_mov_b32_e32 v34, v2
	v_mov_b32_e32 v35, v2
	v_mov_b32_e32 v36, v2
	v_mov_b32_e32 v37, v2
	v_mov_b32_e32 v46, v2
	v_mov_b32_e32 v47, v2
	v_mov_b32_e32 v48, v2
	v_mov_b32_e32 v49, v2
	v_mov_b32_e32 v50, v2
	v_mov_b32_e32 v51, v2
	v_mov_b32_e32 v52, v2
	v_mov_b32_e32 v53, v2
	v_mov_b32_e32 v62, v2
	v_mov_b32_e32 v63, v2
	v_mov_b32_e32 v64, v2
	v_mov_b32_e32 v65, v2
	v_mov_b32_e32 v6, v2
	v_mov_b32_e32 v7, v2
	v_mov_b32_e32 v8, v2
	v_mov_b32_e32 v9, v2
	v_mov_b32_e32 v14, v2
	v_mov_b32_e32 v15, v2
	v_mov_b32_e32 v16, v2
	v_mov_b32_e32 v17, v2
	v_mov_b32_e32 v22, v2
	v_mov_b32_e32 v23, v2
	v_mov_b32_e32 v24, v2
	v_mov_b32_e32 v25, v2
	v_mov_b32_e32 v26, v2
	v_mov_b32_e32 v27, v2
	v_mov_b32_e32 v28, v2
	v_mov_b32_e32 v29, v2
	v_mov_b32_e32 v38, v2
	v_mov_b32_e32 v39, v2
	v_mov_b32_e32 v40, v2
	v_mov_b32_e32 v41, v2
	v_mov_b32_e32 v42, v2
	v_mov_b32_e32 v43, v2
	v_mov_b32_e32 v44, v2
	v_mov_b32_e32 v45, v2
	v_mov_b32_e32 v54, v2
	v_mov_b32_e32 v55, v2
	v_mov_b32_e32 v56, v2
	v_mov_b32_e32 v57, v2
	v_mov_b32_e32 v58, v2
	v_mov_b32_e32 v59, v2
	v_mov_b32_e32 v60, v2
	v_mov_b32_e32 v61, v2
	v_mov_b32_e32 v66, v2
	v_mov_b32_e32 v67, v2
	v_mov_b32_e32 v68, v2
	v_mov_b32_e32 v69, v2
	v_mov_b32_e32 v78, v2
	v_mov_b32_e32 v79, v2
	v_mov_b32_e32 v80, v2
	v_mov_b32_e32 v81, v2
	v_mov_b32_e32 v82, v2
	v_mov_b32_e32 v83, v2
	v_mov_b32_e32 v84, v2
	v_mov_b32_e32 v85, v2
	v_mov_b32_e32 v94, v2
	v_mov_b32_e32 v95, v2
	v_mov_b32_e32 v96, v2
	v_mov_b32_e32 v97, v2
	v_mov_b32_e32 v98, v2
	v_mov_b32_e32 v99, v2
	v_mov_b32_e32 v100, v2
	v_mov_b32_e32 v101, v2
	v_mov_b32_e32 v110, v2
	v_mov_b32_e32 v111, v2
	v_mov_b32_e32 v112, v2
	v_mov_b32_e32 v113, v2
	v_mov_b32_e32 v118, v2
	v_mov_b32_e32 v119, v2
	v_mov_b32_e32 v120, v2
	v_mov_b32_e32 v121, v2
	v_mov_b32_e32 v126, v2
	v_mov_b32_e32 v127, v2
	v_mov_b32_e32 v128, v2
	v_mov_b32_e32 v129, v2
	v_mov_b32_e32 v70, v2
	v_mov_b32_e32 v71, v2
	v_mov_b32_e32 v72, v2
	v_mov_b32_e32 v73, v2
	v_mov_b32_e32 v74, v2
	v_mov_b32_e32 v75, v2
	v_mov_b32_e32 v76, v2
	v_mov_b32_e32 v77, v2
	v_mov_b32_e32 v86, v2
	v_mov_b32_e32 v87, v2
	v_mov_b32_e32 v88, v2
	v_mov_b32_e32 v89, v2
	v_mov_b32_e32 v90, v2
	v_mov_b32_e32 v91, v2
	v_mov_b32_e32 v92, v2
	v_mov_b32_e32 v93, v2
	v_mov_b32_e32 v102, v2
	v_mov_b32_e32 v103, v2
	v_mov_b32_e32 v104, v2
	v_mov_b32_e32 v105, v2
	v_mov_b32_e32 v106, v2
	v_mov_b32_e32 v107, v2
	v_mov_b32_e32 v108, v2
	v_mov_b32_e32 v109, v2
	v_mov_b32_e32 v114, v2
	v_mov_b32_e32 v115, v2
	v_mov_b32_e32 v116, v2
	v_mov_b32_e32 v117, v2
	v_mov_b32_e32 v122, v2
	v_mov_b32_e32 v123, v2
	v_mov_b32_e32 v124, v2
	v_mov_b32_e32 v125, v2
	.p2align 6

.LBB0_293:
	s_add_u32 s18, s18, 0xb0080
	s_addc_u32 s19, s19, 0
	s_add_u32 s49, s20, 0x100
	v_mov_b32_e32 v2, 0
	s_addc_u32 s50, s21, 0
	s_mov_b32 s51, -2
	s_waitcnt lgkmcnt(0)
	v_mov_b32_e32 v3, v2
	v_mov_b32_e32 v4, v2
	v_mov_b32_e32 v5, v2
	v_mov_b32_e32 v6, v2
	v_mov_b32_e32 v7, v2
	v_mov_b32_e32 v8, v2
	v_mov_b32_e32 v9, v2
	v_mov_b32_e32 v18, v2
	v_mov_b32_e32 v19, v2
	v_mov_b32_e32 v20, v2
	v_mov_b32_e32 v21, v2
	v_mov_b32_e32 v22, v2
	v_mov_b32_e32 v23, v2
	v_mov_b32_e32 v24, v2
	v_mov_b32_e32 v25, v2
	v_mov_b32_e32 v34, v2
	v_mov_b32_e32 v35, v2
	v_mov_b32_e32 v36, v2
	v_mov_b32_e32 v37, v2
	v_mov_b32_e32 v38, v2
	v_mov_b32_e32 v39, v2
	v_mov_b32_e32 v40, v2
	v_mov_b32_e32 v41, v2
	v_mov_b32_e32 v50, v2
	v_mov_b32_e32 v51, v2
	v_mov_b32_e32 v52, v2
	v_mov_b32_e32 v53, v2
	v_mov_b32_e32 v54, v2
	v_mov_b32_e32 v55, v2
	v_mov_b32_e32 v56, v2
	v_mov_b32_e32 v57, v2
	v_mov_b32_e32 v10, v2
	v_mov_b32_e32 v11, v2
	v_mov_b32_e32 v12, v2
	v_mov_b32_e32 v13, v2
	v_mov_b32_e32 v14, v2
	v_mov_b32_e32 v15, v2
	v_mov_b32_e32 v16, v2
	v_mov_b32_e32 v17, v2
	v_mov_b32_e32 v26, v2
	v_mov_b32_e32 v27, v2
	v_mov_b32_e32 v28, v2
	v_mov_b32_e32 v29, v2
	v_mov_b32_e32 v30, v2
	v_mov_b32_e32 v31, v2
	v_mov_b32_e32 v32, v2
	v_mov_b32_e32 v33, v2
	v_mov_b32_e32 v42, v2
	v_mov_b32_e32 v43, v2
	v_mov_b32_e32 v44, v2
	v_mov_b32_e32 v45, v2
	v_mov_b32_e32 v46, v2
	v_mov_b32_e32 v47, v2
	v_mov_b32_e32 v48, v2
	v_mov_b32_e32 v49, v2
	v_mov_b32_e32 v58, v2
	v_mov_b32_e32 v59, v2
	v_mov_b32_e32 v60, v2
	v_mov_b32_e32 v61, v2
	v_mov_b32_e32 v62, v2
	v_mov_b32_e32 v63, v2
	v_mov_b32_e32 v64, v2
	v_mov_b32_e32 v65, v2
	v_mov_b32_e32 v66, v2
	v_mov_b32_e32 v67, v2
	v_mov_b32_e32 v68, v2
	v_mov_b32_e32 v69, v2
	v_mov_b32_e32 v70, v2
	v_mov_b32_e32 v71, v2
	v_mov_b32_e32 v72, v2
	v_mov_b32_e32 v73, v2
	v_mov_b32_e32 v82, v2
	v_mov_b32_e32 v83, v2
	v_mov_b32_e32 v84, v2
	v_mov_b32_e32 v85, v2
	v_mov_b32_e32 v86, v2
	v_mov_b32_e32 v87, v2
	v_mov_b32_e32 v88, v2
	v_mov_b32_e32 v89, v2
	v_mov_b32_e32 v98, v2
	v_mov_b32_e32 v99, v2
	v_mov_b32_e32 v100, v2
	v_mov_b32_e32 v101, v2
	v_mov_b32_e32 v102, v2
	v_mov_b32_e32 v103, v2
	v_mov_b32_e32 v104, v2
	v_mov_b32_e32 v105, v2
	v_mov_b32_e32 v114, v2
	v_mov_b32_e32 v115, v2
	v_mov_b32_e32 v116, v2
	v_mov_b32_e32 v117, v2
	v_mov_b32_e32 v118, v2
	v_mov_b32_e32 v119, v2
	v_mov_b32_e32 v120, v2
	v_mov_b32_e32 v121, v2
	v_mov_b32_e32 v74, v2
	v_mov_b32_e32 v75, v2
	v_mov_b32_e32 v76, v2
	v_mov_b32_e32 v77, v2
	v_mov_b32_e32 v78, v2
	v_mov_b32_e32 v79, v2
	v_mov_b32_e32 v80, v2
	v_mov_b32_e32 v81, v2
	v_mov_b32_e32 v90, v2
	v_mov_b32_e32 v91, v2
	v_mov_b32_e32 v92, v2
	v_mov_b32_e32 v93, v2
	v_mov_b32_e32 v94, v2
	v_mov_b32_e32 v95, v2
	v_mov_b32_e32 v96, v2
	v_mov_b32_e32 v97, v2
	v_mov_b32_e32 v106, v2
	v_mov_b32_e32 v107, v2
	v_mov_b32_e32 v108, v2
	v_mov_b32_e32 v109, v2
	v_mov_b32_e32 v110, v2
	v_mov_b32_e32 v111, v2
	v_mov_b32_e32 v112, v2
	v_mov_b32_e32 v113, v2
	v_mov_b32_e32 v122, v2
	v_mov_b32_e32 v123, v2
	v_mov_b32_e32 v124, v2
	v_mov_b32_e32 v125, v2
	v_mov_b32_e32 v126, v2
	v_mov_b32_e32 v127, v2
	v_mov_b32_e32 v128, v2
	v_mov_b32_e32 v129, v2
	.p2align 6

.LBB0_337:
	s_ashr_i32 s35, s34, 31
	s_lshl_b64 s[14:15], s[34:35], 19
	s_add_u32 s36, s33, s14
	s_addc_u32 s37, s40, s15
	s_and_b64 s[14:15], s[8:9], exec
	s_cselect_b32 s1, s37, s11
	s_cselect_b32 s3, s36, s10
	s_ashr_i32 s31, s30, 31
	s_lshl_b64 s[14:15], s[30:31], 19
	s_add_u32 s38, s41, s14
	s_addc_u32 s39, s42, s15
	s_and_b64 s[14:15], s[8:9], exec
	s_cselect_b32 s16, s39, s13
	s_cselect_b32 s17, s38, s12
	s_add_u32 s10, s10, 0x40080
	s_addc_u32 s11, s11, 0
	s_add_u32 s31, s12, 0x100
	v_mov_b32_e32 v66, 0
	s_addc_u32 s35, s13, 0
	s_mov_b32 s72, -2
	v_mov_b32_e32 v67, v66
	v_mov_b32_e32 v68, v66
	v_mov_b32_e32 v69, v66
	v_mov_b32_e32 v70, v66
	v_mov_b32_e32 v71, v66
	v_mov_b32_e32 v72, v66
	v_mov_b32_e32 v73, v66
	v_mov_b32_e32 v74, v66
	v_mov_b32_e32 v75, v66
	v_mov_b32_e32 v76, v66
	v_mov_b32_e32 v77, v66
	v_mov_b32_e32 v78, v66
	v_mov_b32_e32 v79, v66
	v_mov_b32_e32 v80, v66
	v_mov_b32_e32 v81, v66
	v_mov_b32_e32 v98, v66
	v_mov_b32_e32 v99, v66
	v_mov_b32_e32 v100, v66
	v_mov_b32_e32 v101, v66
	v_mov_b32_e32 v102, v66
	v_mov_b32_e32 v103, v66
	v_mov_b32_e32 v104, v66
	v_mov_b32_e32 v105, v66
	v_mov_b32_e32 v106, v66
	v_mov_b32_e32 v107, v66
	v_mov_b32_e32 v108, v66
	v_mov_b32_e32 v109, v66
	v_mov_b32_e32 v110, v66
	v_mov_b32_e32 v111, v66
	v_mov_b32_e32 v112, v66
	v_mov_b32_e32 v113, v66
	v_mov_b32_e32 v2, v66
	v_mov_b32_e32 v3, v66
	v_mov_b32_e32 v4, v66
	v_mov_b32_e32 v5, v66
	v_mov_b32_e32 v6, v66
	v_mov_b32_e32 v7, v66
	v_mov_b32_e32 v8, v66
	v_mov_b32_e32 v9, v66
	v_mov_b32_e32 v10, v66
	v_mov_b32_e32 v11, v66
	v_mov_b32_e32 v12, v66
	v_mov_b32_e32 v13, v66
	v_mov_b32_e32 v14, v66
	v_mov_b32_e32 v15, v66
	v_mov_b32_e32 v16, v66
	v_mov_b32_e32 v17, v66
	v_mov_b32_e32 v18, v66
	v_mov_b32_e32 v19, v66
	v_mov_b32_e32 v20, v66
	v_mov_b32_e32 v21, v66
	v_mov_b32_e32 v22, v66
	v_mov_b32_e32 v23, v66
	v_mov_b32_e32 v24, v66
	v_mov_b32_e32 v25, v66
	v_mov_b32_e32 v26, v66
	v_mov_b32_e32 v27, v66
	v_mov_b32_e32 v28, v66
	v_mov_b32_e32 v29, v66
	v_mov_b32_e32 v30, v66
	v_mov_b32_e32 v31, v66
	v_mov_b32_e32 v32, v66
	v_mov_b32_e32 v33, v66
	v_mov_b32_e32 v114, v66
	v_mov_b32_e32 v115, v66
	v_mov_b32_e32 v116, v66
	v_mov_b32_e32 v117, v66
	v_mov_b32_e32 v118, v66
	v_mov_b32_e32 v119, v66
	v_mov_b32_e32 v120, v66
	v_mov_b32_e32 v121, v66
	v_mov_b32_e32 v122, v66
	v_mov_b32_e32 v123, v66
	v_mov_b32_e32 v124, v66
	v_mov_b32_e32 v125, v66
	v_mov_b32_e32 v126, v66
	v_mov_b32_e32 v127, v66
	v_mov_b32_e32 v128, v66
	v_mov_b32_e32 v129, v66
	v_mov_b32_e32 v130, v66
	v_mov_b32_e32 v131, v66
	v_mov_b32_e32 v132, v66
	v_mov_b32_e32 v133, v66
	v_mov_b32_e32 v134, v66
	v_mov_b32_e32 v135, v66
	v_mov_b32_e32 v136, v66
	v_mov_b32_e32 v137, v66
	v_mov_b32_e32 v138, v66
	v_mov_b32_e32 v139, v66
	v_mov_b32_e32 v140, v66
	v_mov_b32_e32 v141, v66
	v_mov_b32_e32 v142, v66
	v_mov_b32_e32 v143, v66
	v_mov_b32_e32 v144, v66
	v_mov_b32_e32 v145, v66
	v_mov_b32_e32 v34, v66
	v_mov_b32_e32 v35, v66
	v_mov_b32_e32 v36, v66
	v_mov_b32_e32 v37, v66
	v_mov_b32_e32 v38, v66
	v_mov_b32_e32 v39, v66
	v_mov_b32_e32 v40, v66
	v_mov_b32_e32 v41, v66
	v_mov_b32_e32 v42, v66
	v_mov_b32_e32 v43, v66
	v_mov_b32_e32 v44, v66
	v_mov_b32_e32 v45, v66
	v_mov_b32_e32 v46, v66
	v_mov_b32_e32 v47, v66
	v_mov_b32_e32 v48, v66
	v_mov_b32_e32 v49, v66
	v_mov_b32_e32 v50, v66
	v_mov_b32_e32 v51, v66
	v_mov_b32_e32 v52, v66
	v_mov_b32_e32 v53, v66
	v_mov_b32_e32 v54, v66
	v_mov_b32_e32 v55, v66
	v_mov_b32_e32 v56, v66
	v_mov_b32_e32 v57, v66
	v_mov_b32_e32 v58, v66
	v_mov_b32_e32 v59, v66
	v_mov_b32_e32 v60, v66
	v_mov_b32_e32 v61, v66
	v_mov_b32_e32 v62, v66
	v_mov_b32_e32 v63, v66
	v_mov_b32_e32 v64, v66
	v_mov_b32_e32 v65, v66
	.p2align 6

.LBB0_795:
	s_lshl_b32 s6, s6, 4
	s_sub_i32 s7, s3, s6
	s_min_i32 s6, s7, 16
	s_cmp_lt_i32 s7, 4
	s_mov_b32 s7, 0
	s_cbranch_scc1 .LBB0_798
	v_mov_b32_e32 v139, v137
	v_mov_b32_e32 v148, v136
	.p2align 6

.LBB0_2386:
	s_ashr_i32 s17, s16, 31
	v_cmp_lt_i64_e32 vcc, s[18:19], v[190:191]
	s_lshl_b64 s[18:19], s[16:17], 19
	s_add_u32 s18, s33, s18
	s_addc_u32 s19, s34, s19
	s_and_b64 s[20:21], vcc, exec
	s_cselect_b32 s17, s19, s25
	s_cselect_b32 s23, s18, s24
	s_ashr_i32 s15, s14, 31
	s_lshl_b64 s[20:21], s[14:15], 19
	s_add_u32 s20, s35, s20
	s_addc_u32 s21, s36, s21
	s_and_b64 s[28:29], vcc, exec
	s_cselect_b32 s15, s21, s27
	s_cselect_b32 s52, s20, s26
	s_add_u32 s24, s24, 0x40080
	s_addc_u32 s25, s25, 0
	s_add_u32 s53, s26, 0x100
	v_mov_b32_e32 v2, 0
	s_addc_u32 s54, s27, 0
	s_mov_b32 s55, -2
	s_waitcnt lgkmcnt(0)
	v_mov_b32_e32 v3, v2
	v_mov_b32_e32 v4, v2
	v_mov_b32_e32 v5, v2
	v_mov_b32_e32 v6, v2
	v_mov_b32_e32 v7, v2
	v_mov_b32_e32 v8, v2
	v_mov_b32_e32 v9, v2
	v_mov_b32_e32 v18, v2
	v_mov_b32_e32 v19, v2
	v_mov_b32_e32 v20, v2
	v_mov_b32_e32 v21, v2
	v_mov_b32_e32 v22, v2
	v_mov_b32_e32 v23, v2
	v_mov_b32_e32 v24, v2
	v_mov_b32_e32 v25, v2
	s_waitcnt vmcnt(0)
	v_mov_b32_e32 v34, v2
	v_mov_b32_e32 v35, v2
	v_mov_b32_e32 v36, v2
	v_mov_b32_e32 v37, v2
	v_mov_b32_e32 v38, v2
	v_mov_b32_e32 v39, v2
	v_mov_b32_e32 v40, v2
	v_mov_b32_e32 v41, v2
	v_mov_b32_e32 v50, v2
	v_mov_b32_e32 v51, v2
	v_mov_b32_e32 v52, v2
	v_mov_b32_e32 v53, v2
	v_mov_b32_e32 v54, v2
	v_mov_b32_e32 v55, v2
	v_mov_b32_e32 v56, v2
	v_mov_b32_e32 v57, v2
	v_mov_b32_e32 v10, v2
	v_mov_b32_e32 v11, v2
	v_mov_b32_e32 v12, v2
	v_mov_b32_e32 v13, v2
	v_mov_b32_e32 v14, v2
	v_mov_b32_e32 v15, v2
	v_mov_b32_e32 v16, v2
	v_mov_b32_e32 v17, v2
	v_mov_b32_e32 v26, v2
	v_mov_b32_e32 v27, v2
	v_mov_b32_e32 v28, v2
	v_mov_b32_e32 v29, v2
	v_mov_b32_e32 v30, v2
	v_mov_b32_e32 v31, v2
	v_mov_b32_e32 v32, v2
	v_mov_b32_e32 v33, v2
	v_mov_b32_e32 v42, v2
	v_mov_b32_e32 v43, v2
	v_mov_b32_e32 v44, v2
	v_mov_b32_e32 v45, v2
	v_mov_b32_e32 v46, v2
	v_mov_b32_e32 v47, v2
	v_mov_b32_e32 v48, v2
	v_mov_b32_e32 v49, v2
	v_mov_b32_e32 v58, v2
	v_mov_b32_e32 v59, v2
	v_mov_b32_e32 v60, v2
	v_mov_b32_e32 v61, v2
	v_mov_b32_e32 v62, v2
	v_mov_b32_e32 v63, v2
	v_mov_b32_e32 v64, v2
	v_mov_b32_e32 v65, v2
	v_mov_b32_e32 v66, v2
	v_mov_b32_e32 v67, v2
	v_mov_b32_e32 v68, v2
	v_mov_b32_e32 v69, v2
	v_mov_b32_e32 v70, v2
	v_mov_b32_e32 v71, v2
	v_mov_b32_e32 v72, v2
	v_mov_b32_e32 v73, v2
	v_mov_b32_e32 v82, v2
	v_mov_b32_e32 v83, v2
	v_mov_b32_e32 v84, v2
	v_mov_b32_e32 v85, v2
	v_mov_b32_e32 v86, v2
	v_mov_b32_e32 v87, v2
	v_mov_b32_e32 v88, v2
	v_mov_b32_e32 v89, v2
	v_mov_b32_e32 v98, v2
	v_mov_b32_e32 v99, v2
	v_mov_b32_e32 v100, v2
	v_mov_b32_e32 v101, v2
	v_mov_b32_e32 v102, v2
	v_mov_b32_e32 v103, v2
	v_mov_b32_e32 v104, v2
	v_mov_b32_e32 v105, v2
	v_mov_b32_e32 v114, v2
	v_mov_b32_e32 v115, v2
	v_mov_b32_e32 v116, v2
	v_mov_b32_e32 v117, v2
	v_mov_b32_e32 v118, v2
	v_mov_b32_e32 v119, v2
	v_mov_b32_e32 v120, v2
	v_mov_b32_e32 v121, v2
	v_mov_b32_e32 v74, v2
	v_mov_b32_e32 v75, v2
	v_mov_b32_e32 v76, v2
	v_mov_b32_e32 v77, v2
	v_mov_b32_e32 v78, v2
	v_mov_b32_e32 v79, v2
	v_mov_b32_e32 v80, v2
	v_mov_b32_e32 v81, v2
	v_mov_b32_e32 v90, v2
	v_mov_b32_e32 v91, v2
	v_mov_b32_e32 v92, v2
	v_mov_b32_e32 v93, v2
	v_mov_b32_e32 v94, v2
	v_mov_b32_e32 v95, v2
	v_mov_b32_e32 v96, v2
	v_mov_b32_e32 v97, v2
	v_mov_b32_e32 v106, v2
	v_mov_b32_e32 v107, v2
	v_mov_b32_e32 v108, v2
	v_mov_b32_e32 v109, v2
	v_mov_b32_e32 v110, v2
	v_mov_b32_e32 v111, v2
	v_mov_b32_e32 v112, v2
	v_mov_b32_e32 v113, v2
	v_mov_b32_e32 v122, v2
	v_mov_b32_e32 v123, v2
	v_mov_b32_e32 v124, v2
	v_mov_b32_e32 v125, v2
	v_mov_b32_e32 v126, v2
	v_mov_b32_e32 v127, v2
	v_mov_b32_e32 v128, v2
	v_mov_b32_e32 v129, v2
	.p2align 6

.LBB0_2428:
	s_ashr_i32 s19, s18, 31
	s_lshl_b64 s[20:21], s[18:19], 19
	s_add_u32 s20, s30, s20
	s_addc_u32 s21, s31, s21
	s_and_b64 s[22:23], s[4:5], exec
	s_cselect_b32 s19, s21, s25
	s_cselect_b32 s53, s20, s24
	s_ashr_i32 s17, s16, 31
	s_lshl_b64 s[22:23], s[16:17], 19
	s_add_u32 s22, s33, s22
	s_addc_u32 s23, s34, s23
	s_and_b64 s[28:29], s[4:5], exec
	s_cselect_b32 s17, s23, s27
	s_cselect_b32 s54, s22, s26
	s_add_u32 s24, s24, 0x40080
	s_addc_u32 s25, s25, 0
	s_add_u32 s55, s26, 0x100
	v_mov_b32_e32 v2, 0
	s_addc_u32 s56, s27, 0
	s_mov_b32 s57, -2
	v_mov_b32_e32 v3, v2
	v_mov_b32_e32 v4, v2
	v_mov_b32_e32 v5, v2
	v_mov_b32_e32 v10, v2
	v_mov_b32_e32 v11, v2
	v_mov_b32_e32 v12, v2
	v_mov_b32_e32 v13, v2
	v_mov_b32_e32 v18, v2
	v_mov_b32_e32 v19, v2
	v_mov_b32_e32 v20, v2
	v_mov_b32_e32 v21, v2
	v_mov_b32_e32 v30, v2
	v_mov_b32_e32 v31, v2
	v_mov_b32_e32 v32, v2
	v_mov_b32_e32 v33, v2
	s_waitcnt vmcnt(0)
	v_mov_b32_e32 v34, v2
	v_mov_b32_e32 v35, v2
	v_mov_b32_e32 v36, v2
	v_mov_b32_e32 v37, v2
	v_mov_b32_e32 v46, v2
	v_mov_b32_e32 v47, v2
	v_mov_b32_e32 v48, v2
	v_mov_b32_e32 v49, v2
	v_mov_b32_e32 v50, v2
	v_mov_b32_e32 v51, v2
	v_mov_b32_e32 v52, v2
	v_mov_b32_e32 v53, v2
	v_mov_b32_e32 v62, v2
	v_mov_b32_e32 v63, v2
	v_mov_b32_e32 v64, v2
	v_mov_b32_e32 v65, v2
	v_mov_b32_e32 v6, v2
	v_mov_b32_e32 v7, v2
	v_mov_b32_e32 v8, v2
	v_mov_b32_e32 v9, v2
	v_mov_b32_e32 v14, v2
	v_mov_b32_e32 v15, v2
	v_mov_b32_e32 v16, v2
	v_mov_b32_e32 v17, v2
	v_mov_b32_e32 v22, v2
	v_mov_b32_e32 v23, v2
	v_mov_b32_e32 v24, v2
	v_mov_b32_e32 v25, v2
	v_mov_b32_e32 v26, v2
	v_mov_b32_e32 v27, v2
	v_mov_b32_e32 v28, v2
	v_mov_b32_e32 v29, v2
	v_mov_b32_e32 v38, v2
	v_mov_b32_e32 v39, v2
	v_mov_b32_e32 v40, v2
	v_mov_b32_e32 v41, v2
	v_mov_b32_e32 v42, v2
	v_mov_b32_e32 v43, v2
	v_mov_b32_e32 v44, v2
	v_mov_b32_e32 v45, v2
	v_mov_b32_e32 v54, v2
	v_mov_b32_e32 v55, v2
	v_mov_b32_e32 v56, v2
	v_mov_b32_e32 v57, v2
	v_mov_b32_e32 v58, v2
	v_mov_b32_e32 v59, v2
	v_mov_b32_e32 v60, v2
	v_mov_b32_e32 v61, v2
	v_mov_b32_e32 v66, v2
	v_mov_b32_e32 v67, v2
	v_mov_b32_e32 v68, v2
	v_mov_b32_e32 v69, v2
	v_mov_b32_e32 v78, v2
	v_mov_b32_e32 v79, v2
	v_mov_b32_e32 v80, v2
	v_mov_b32_e32 v81, v2
	v_mov_b32_e32 v82, v2
	v_mov_b32_e32 v83, v2
	v_mov_b32_e32 v84, v2
	v_mov_b32_e32 v85, v2
	v_mov_b32_e32 v94, v2
	v_mov_b32_e32 v95, v2
	v_mov_b32_e32 v96, v2
	v_mov_b32_e32 v97, v2
	v_mov_b32_e32 v98, v2
	v_mov_b32_e32 v99, v2
	v_mov_b32_e32 v100, v2
	v_mov_b32_e32 v101, v2
	v_mov_b32_e32 v110, v2
	v_mov_b32_e32 v111, v2
	v_mov_b32_e32 v112, v2
	v_mov_b32_e32 v113, v2
	v_mov_b32_e32 v118, v2
	v_mov_b32_e32 v119, v2
	v_mov_b32_e32 v120, v2
	v_mov_b32_e32 v121, v2
	v_mov_b32_e32 v126, v2
	v_mov_b32_e32 v127, v2
	v_mov_b32_e32 v128, v2
	v_mov_b32_e32 v129, v2
	v_mov_b32_e32 v70, v2
	v_mov_b32_e32 v71, v2
	v_mov_b32_e32 v72, v2
	v_mov_b32_e32 v73, v2
	v_mov_b32_e32 v74, v2
	v_mov_b32_e32 v75, v2
	v_mov_b32_e32 v76, v2
	v_mov_b32_e32 v77, v2
	v_mov_b32_e32 v86, v2
	v_mov_b32_e32 v87, v2
	v_mov_b32_e32 v88, v2
	v_mov_b32_e32 v89, v2
	v_mov_b32_e32 v90, v2
	v_mov_b32_e32 v91, v2
	v_mov_b32_e32 v92, v2
	v_mov_b32_e32 v93, v2
	v_mov_b32_e32 v102, v2
	v_mov_b32_e32 v103, v2
	v_mov_b32_e32 v104, v2
	v_mov_b32_e32 v105, v2
	v_mov_b32_e32 v106, v2
	v_mov_b32_e32 v107, v2
	v_mov_b32_e32 v108, v2
	v_mov_b32_e32 v109, v2
	v_mov_b32_e32 v114, v2
	v_mov_b32_e32 v115, v2
	v_mov_b32_e32 v116, v2
	v_mov_b32_e32 v117, v2
	v_mov_b32_e32 v122, v2
	v_mov_b32_e32 v123, v2
	v_mov_b32_e32 v124, v2
	v_mov_b32_e32 v125, v2
	.p2align 6

.LBB0_2470:
	s_add_u32 s18, s18, 0xb0080
	s_addc_u32 s19, s19, 0
	s_add_u32 s49, s20, 0x100
	v_mov_b32_e32 v2, 0
	s_addc_u32 s50, s21, 0
	s_mov_b32 s51, -2
	s_waitcnt lgkmcnt(0)
	v_mov_b32_e32 v3, v2
	v_mov_b32_e32 v4, v2
	v_mov_b32_e32 v5, v2
	v_mov_b32_e32 v6, v2
	v_mov_b32_e32 v7, v2
	v_mov_b32_e32 v8, v2
	v_mov_b32_e32 v9, v2
	v_mov_b32_e32 v18, v2
	v_mov_b32_e32 v19, v2
	v_mov_b32_e32 v20, v2
	v_mov_b32_e32 v21, v2
	v_mov_b32_e32 v22, v2
	v_mov_b32_e32 v23, v2
	v_mov_b32_e32 v24, v2
	v_mov_b32_e32 v25, v2
	s_waitcnt vmcnt(0)
	v_mov_b32_e32 v34, v2
	v_mov_b32_e32 v35, v2
	v_mov_b32_e32 v36, v2
	v_mov_b32_e32 v37, v2
	v_mov_b32_e32 v38, v2
	v_mov_b32_e32 v39, v2
	v_mov_b32_e32 v40, v2
	v_mov_b32_e32 v41, v2
	v_mov_b32_e32 v50, v2
	v_mov_b32_e32 v51, v2
	v_mov_b32_e32 v52, v2
	v_mov_b32_e32 v53, v2
	v_mov_b32_e32 v54, v2
	v_mov_b32_e32 v55, v2
	v_mov_b32_e32 v56, v2
	v_mov_b32_e32 v57, v2
	v_mov_b32_e32 v10, v2
	v_mov_b32_e32 v11, v2
	v_mov_b32_e32 v12, v2
	v_mov_b32_e32 v13, v2
	v_mov_b32_e32 v14, v2
	v_mov_b32_e32 v15, v2
	v_mov_b32_e32 v16, v2
	v_mov_b32_e32 v17, v2
	v_mov_b32_e32 v26, v2
	v_mov_b32_e32 v27, v2
	v_mov_b32_e32 v28, v2
	v_mov_b32_e32 v29, v2
	v_mov_b32_e32 v30, v2
	v_mov_b32_e32 v31, v2
	v_mov_b32_e32 v32, v2
	v_mov_b32_e32 v33, v2
	v_mov_b32_e32 v42, v2
	v_mov_b32_e32 v43, v2
	v_mov_b32_e32 v44, v2
	v_mov_b32_e32 v45, v2
	v_mov_b32_e32 v46, v2
	v_mov_b32_e32 v47, v2
	v_mov_b32_e32 v48, v2
	v_mov_b32_e32 v49, v2
	v_mov_b32_e32 v58, v2
	v_mov_b32_e32 v59, v2
	v_mov_b32_e32 v60, v2
	v_mov_b32_e32 v61, v2
	v_mov_b32_e32 v62, v2
	v_mov_b32_e32 v63, v2
	v_mov_b32_e32 v64, v2
	v_mov_b32_e32 v65, v2
	v_mov_b32_e32 v66, v2
	v_mov_b32_e32 v67, v2
	v_mov_b32_e32 v68, v2
	v_mov_b32_e32 v69, v2
	v_mov_b32_e32 v70, v2
	v_mov_b32_e32 v71, v2
	v_mov_b32_e32 v72, v2
	v_mov_b32_e32 v73, v2
	v_mov_b32_e32 v82, v2
	v_mov_b32_e32 v83, v2
	v_mov_b32_e32 v84, v2
	v_mov_b32_e32 v85, v2
	v_mov_b32_e32 v86, v2
	v_mov_b32_e32 v87, v2
	v_mov_b32_e32 v88, v2
	v_mov_b32_e32 v89, v2
	v_mov_b32_e32 v98, v2
	v_mov_b32_e32 v99, v2
	v_mov_b32_e32 v100, v2
	v_mov_b32_e32 v101, v2
	v_mov_b32_e32 v102, v2
	v_mov_b32_e32 v103, v2
	v_mov_b32_e32 v104, v2
	v_mov_b32_e32 v105, v2
	v_mov_b32_e32 v114, v2
	v_mov_b32_e32 v115, v2
	v_mov_b32_e32 v116, v2
	v_mov_b32_e32 v117, v2
	v_mov_b32_e32 v118, v2
	v_mov_b32_e32 v119, v2
	v_mov_b32_e32 v120, v2
	v_mov_b32_e32 v121, v2
	v_mov_b32_e32 v74, v2
	v_mov_b32_e32 v75, v2
	v_mov_b32_e32 v76, v2
	v_mov_b32_e32 v77, v2
	v_mov_b32_e32 v78, v2
	v_mov_b32_e32 v79, v2
	v_mov_b32_e32 v80, v2
	v_mov_b32_e32 v81, v2
	v_mov_b32_e32 v90, v2
	v_mov_b32_e32 v91, v2
	v_mov_b32_e32 v92, v2
	v_mov_b32_e32 v93, v2
	v_mov_b32_e32 v94, v2
	v_mov_b32_e32 v95, v2
	v_mov_b32_e32 v96, v2
	v_mov_b32_e32 v97, v2
	v_mov_b32_e32 v106, v2
	v_mov_b32_e32 v107, v2
	v_mov_b32_e32 v108, v2
	v_mov_b32_e32 v109, v2
	v_mov_b32_e32 v110, v2
	v_mov_b32_e32 v111, v2
	v_mov_b32_e32 v112, v2
	v_mov_b32_e32 v113, v2
	v_mov_b32_e32 v122, v2
	v_mov_b32_e32 v123, v2
	v_mov_b32_e32 v124, v2
	v_mov_b32_e32 v125, v2
	v_mov_b32_e32 v126, v2
	v_mov_b32_e32 v127, v2
	v_mov_b32_e32 v128, v2
	v_mov_b32_e32 v129, v2
	.p2align 6

.LBB0_2598:
	s_ashr_i32 s45, s44, 31
	s_lshl_b64 s[14:15], s[44:45], 19
	s_add_u32 s46, s33, s14
	s_addc_u32 s47, s50, s15
	s_and_b64 s[14:15], s[96:97], exec
	s_cselect_b32 s1, s47, s11
	s_cselect_b32 s3, s46, s10
	s_ashr_i32 s43, s42, 31
	s_lshl_b64 s[14:15], s[42:43], 19
	s_add_u32 s48, s51, s14
	s_addc_u32 s49, s52, s15
	s_and_b64 s[14:15], s[96:97], exec
	s_cselect_b32 s16, s49, s13
	s_cselect_b32 s17, s48, s12
	s_add_u32 s10, s10, 0x40080
	s_addc_u32 s11, s11, 0
	s_add_u32 s43, s12, 0x100
	v_mov_b32_e32 v66, 0
	s_addc_u32 s45, s13, 0
	s_mov_b32 s84, -2
	v_mov_b32_e32 v67, v66
	v_mov_b32_e32 v68, v66
	v_mov_b32_e32 v69, v66
	v_mov_b32_e32 v70, v66
	v_mov_b32_e32 v71, v66
	v_mov_b32_e32 v72, v66
	v_mov_b32_e32 v73, v66
	v_mov_b32_e32 v74, v66
	v_mov_b32_e32 v75, v66
	v_mov_b32_e32 v76, v66
	v_mov_b32_e32 v77, v66
	v_mov_b32_e32 v78, v66
	v_mov_b32_e32 v79, v66
	v_mov_b32_e32 v80, v66
	v_mov_b32_e32 v81, v66
	v_mov_b32_e32 v98, v66
	v_mov_b32_e32 v99, v66
	v_mov_b32_e32 v100, v66
	v_mov_b32_e32 v101, v66
	v_mov_b32_e32 v102, v66
	v_mov_b32_e32 v103, v66
	v_mov_b32_e32 v104, v66
	v_mov_b32_e32 v105, v66
	v_mov_b32_e32 v106, v66
	v_mov_b32_e32 v107, v66
	v_mov_b32_e32 v108, v66
	v_mov_b32_e32 v109, v66
	v_mov_b32_e32 v110, v66
	v_mov_b32_e32 v111, v66
	v_mov_b32_e32 v112, v66
	v_mov_b32_e32 v113, v66
	v_mov_b32_e32 v2, v66
	v_mov_b32_e32 v3, v66
	v_mov_b32_e32 v4, v66
	v_mov_b32_e32 v5, v66
	v_mov_b32_e32 v6, v66
	v_mov_b32_e32 v7, v66
	v_mov_b32_e32 v8, v66
	v_mov_b32_e32 v9, v66
	v_mov_b32_e32 v10, v66
	v_mov_b32_e32 v11, v66
	v_mov_b32_e32 v12, v66
	v_mov_b32_e32 v13, v66
	v_mov_b32_e32 v14, v66
	v_mov_b32_e32 v15, v66
	v_mov_b32_e32 v16, v66
	v_mov_b32_e32 v17, v66
	v_mov_b32_e32 v18, v66
	v_mov_b32_e32 v19, v66
	v_mov_b32_e32 v20, v66
	v_mov_b32_e32 v21, v66
	v_mov_b32_e32 v22, v66
	v_mov_b32_e32 v23, v66
	v_mov_b32_e32 v24, v66
	v_mov_b32_e32 v25, v66
	v_mov_b32_e32 v26, v66
	v_mov_b32_e32 v27, v66
	v_mov_b32_e32 v28, v66
	v_mov_b32_e32 v29, v66
	v_mov_b32_e32 v30, v66
	v_mov_b32_e32 v31, v66
	v_mov_b32_e32 v32, v66
	v_mov_b32_e32 v33, v66
	v_mov_b32_e32 v114, v66
	v_mov_b32_e32 v115, v66
	v_mov_b32_e32 v116, v66
	v_mov_b32_e32 v117, v66
	v_mov_b32_e32 v118, v66
	v_mov_b32_e32 v119, v66
	v_mov_b32_e32 v120, v66
	v_mov_b32_e32 v121, v66
	v_mov_b32_e32 v122, v66
	v_mov_b32_e32 v123, v66
	v_mov_b32_e32 v124, v66
	v_mov_b32_e32 v125, v66
	v_mov_b32_e32 v126, v66
	v_mov_b32_e32 v127, v66
	v_mov_b32_e32 v128, v66
	v_mov_b32_e32 v129, v66
	v_mov_b32_e32 v130, v66
	v_mov_b32_e32 v131, v66
	v_mov_b32_e32 v132, v66
	v_mov_b32_e32 v133, v66
	v_mov_b32_e32 v134, v66
	v_mov_b32_e32 v135, v66
	v_mov_b32_e32 v136, v66
	v_mov_b32_e32 v137, v66
	v_mov_b32_e32 v138, v66
	v_mov_b32_e32 v139, v66
	v_mov_b32_e32 v140, v66
	v_mov_b32_e32 v141, v66
	v_mov_b32_e32 v142, v66
	v_mov_b32_e32 v143, v66
	v_mov_b32_e32 v144, v66
	v_mov_b32_e32 v145, v66
	s_waitcnt vmcnt(0)
	v_mov_b32_e32 v34, v66
	v_mov_b32_e32 v35, v66
	v_mov_b32_e32 v36, v66
	v_mov_b32_e32 v37, v66
	v_mov_b32_e32 v38, v66
	v_mov_b32_e32 v39, v66
	v_mov_b32_e32 v40, v66
	v_mov_b32_e32 v41, v66
	v_mov_b32_e32 v42, v66
	v_mov_b32_e32 v43, v66
	v_mov_b32_e32 v44, v66
	v_mov_b32_e32 v45, v66
	v_mov_b32_e32 v46, v66
	v_mov_b32_e32 v47, v66
	v_mov_b32_e32 v48, v66
	v_mov_b32_e32 v49, v66
	v_mov_b32_e32 v50, v66
	v_mov_b32_e32 v51, v66
	v_mov_b32_e32 v52, v66
	v_mov_b32_e32 v53, v66
	v_mov_b32_e32 v54, v66
	v_mov_b32_e32 v55, v66
	v_mov_b32_e32 v56, v66
	v_mov_b32_e32 v57, v66
	v_mov_b32_e32 v58, v66
	v_mov_b32_e32 v59, v66
	v_mov_b32_e32 v60, v66
	v_mov_b32_e32 v61, v66
	v_mov_b32_e32 v62, v66
	v_mov_b32_e32 v63, v66
	v_mov_b32_e32 v64, v66
	v_mov_b32_e32 v65, v66
	.p2align 6

.LBB0_3054:
	s_lshl_b32 s8, s8, 4
	s_sub_i32 s9, s5, s8
	s_min_i32 s8, s9, 16
	s_cmp_lt_i32 s9, 4
	s_mov_b32 s9, 0
	s_cbranch_scc1 .LBB0_3057
	v_mov_b32_e32 v161, v159
	v_mov_b32_e32 v148, v158
	.p2align 6

.LBB0_4726:
	s_add_u32 s18, s18, 0xb0080
	s_addc_u32 s19, s19, 0
	s_add_u32 s49, s20, 0x100
	v_mov_b32_e32 v2, 0
	s_addc_u32 s50, s21, 0
	s_mov_b32 s51, -2
	v_mov_b32_e32 v3, v2
	v_mov_b32_e32 v4, v2
	v_mov_b32_e32 v5, v2
	v_mov_b32_e32 v6, v2
	v_mov_b32_e32 v7, v2
	v_mov_b32_e32 v8, v2
	v_mov_b32_e32 v9, v2
	v_mov_b32_e32 v10, v2
	v_mov_b32_e32 v11, v2
	v_mov_b32_e32 v12, v2
	v_mov_b32_e32 v13, v2
	v_mov_b32_e32 v18, v2
	v_mov_b32_e32 v19, v2
	v_mov_b32_e32 v20, v2
	v_mov_b32_e32 v21, v2
	v_mov_b32_e32 v26, v2
	v_mov_b32_e32 v27, v2
	v_mov_b32_e32 v28, v2
	v_mov_b32_e32 v29, v2
	s_waitcnt vmcnt(0)
	v_mov_b32_e32 v34, v2
	v_mov_b32_e32 v35, v2
	v_mov_b32_e32 v36, v2
	v_mov_b32_e32 v37, v2
	v_mov_b32_e32 v42, v2
	v_mov_b32_e32 v43, v2
	v_mov_b32_e32 v44, v2
	v_mov_b32_e32 v45, v2
	v_mov_b32_e32 v50, v2
	v_mov_b32_e32 v51, v2
	v_mov_b32_e32 v52, v2
	v_mov_b32_e32 v53, v2
	v_mov_b32_e32 v14, v2
	v_mov_b32_e32 v15, v2
	v_mov_b32_e32 v16, v2
	v_mov_b32_e32 v17, v2
	v_mov_b32_e32 v22, v2
	v_mov_b32_e32 v23, v2
	v_mov_b32_e32 v24, v2
	v_mov_b32_e32 v25, v2
	v_mov_b32_e32 v30, v2
	v_mov_b32_e32 v31, v2
	v_mov_b32_e32 v32, v2
	v_mov_b32_e32 v33, v2
	v_mov_b32_e32 v38, v2
	v_mov_b32_e32 v39, v2
	v_mov_b32_e32 v40, v2
	v_mov_b32_e32 v41, v2
	v_mov_b32_e32 v46, v2
	v_mov_b32_e32 v47, v2
	v_mov_b32_e32 v48, v2
	v_mov_b32_e32 v49, v2
	v_mov_b32_e32 v54, v2
	v_mov_b32_e32 v55, v2
	v_mov_b32_e32 v56, v2
	v_mov_b32_e32 v57, v2
	v_mov_b32_e32 v58, v2
	v_mov_b32_e32 v59, v2
	v_mov_b32_e32 v60, v2
	v_mov_b32_e32 v61, v2
	v_mov_b32_e32 v62, v2
	v_mov_b32_e32 v63, v2
	v_mov_b32_e32 v64, v2
	v_mov_b32_e32 v65, v2
	v_mov_b32_e32 v66, v2
	v_mov_b32_e32 v67, v2
	v_mov_b32_e32 v68, v2
	v_mov_b32_e32 v69, v2
	v_mov_b32_e32 v70, v2
	v_mov_b32_e32 v71, v2
	v_mov_b32_e32 v72, v2
	v_mov_b32_e32 v73, v2
	v_mov_b32_e32 v74, v2
	v_mov_b32_e32 v75, v2
	v_mov_b32_e32 v76, v2
	v_mov_b32_e32 v77, v2
	v_mov_b32_e32 v78, v2
	v_mov_b32_e32 v79, v2
	v_mov_b32_e32 v80, v2
	v_mov_b32_e32 v81, v2
	v_mov_b32_e32 v86, v2
	v_mov_b32_e32 v87, v2
	v_mov_b32_e32 v88, v2
	v_mov_b32_e32 v89, v2
	v_mov_b32_e32 v94, v2
	v_mov_b32_e32 v95, v2
	v_mov_b32_e32 v96, v2
	v_mov_b32_e32 v97, v2
	v_mov_b32_e32 v102, v2
	v_mov_b32_e32 v103, v2
	v_mov_b32_e32 v104, v2
	v_mov_b32_e32 v105, v2
	v_mov_b32_e32 v110, v2
	v_mov_b32_e32 v111, v2
	v_mov_b32_e32 v112, v2
	v_mov_b32_e32 v113, v2
	v_mov_b32_e32 v82, v2
	v_mov_b32_e32 v83, v2
	v_mov_b32_e32 v84, v2
	v_mov_b32_e32 v85, v2
	v_mov_b32_e32 v90, v2
	v_mov_b32_e32 v91, v2
	v_mov_b32_e32 v92, v2
	v_mov_b32_e32 v93, v2
	v_mov_b32_e32 v98, v2
	v_mov_b32_e32 v99, v2
	v_mov_b32_e32 v100, v2
	v_mov_b32_e32 v101, v2
	v_mov_b32_e32 v106, v2
	v_mov_b32_e32 v107, v2
	v_mov_b32_e32 v108, v2
	v_mov_b32_e32 v109, v2
	v_mov_b32_e32 v114, v2
	v_mov_b32_e32 v115, v2
	v_mov_b32_e32 v116, v2
	v_mov_b32_e32 v117, v2
	v_mov_b32_e32 v118, v2
	v_mov_b32_e32 v119, v2
	v_mov_b32_e32 v120, v2
	v_mov_b32_e32 v121, v2
	v_mov_b32_e32 v122, v2
	v_mov_b32_e32 v123, v2
	v_mov_b32_e32 v124, v2
	v_mov_b32_e32 v125, v2
	v_mov_b32_e32 v126, v2
	v_mov_b32_e32 v127, v2
	v_mov_b32_e32 v128, v2
	v_mov_b32_e32 v129, v2
	.p2align 6
